# P2 and P8 (SwiGLU) epilogue stores marked nt (A/B)
# baseline (speedup 1.0000x reference)
.LBB0_101:
	s_cmp_lt_i32 s29, 6
	s_mov_b32 s30, 0x3e00000
	s_cselect_b32 s19, 0, 0xfffffa00
	s_cselect_b32 s30, s30, 0x6e00000
	v_lshl_or_b32 v144, s29, 8, v141
	s_add_u32 s30, s12, s30
	v_add_u32_e32 v144, s19, v144
	s_addc_u32 s31, s13, 0
	v_ashrrev_i32_e32 v145, 31, v144
	v_lshl_add_u32 v143, s46, 8, v139
	v_lshl_add_u64 v[144:145], v[144:145], 1, s[30:31]
	v_mad_i64_i32 v[146:147], s[30:31], v143, s91, v[144:145]
	v_cvt_pk_bf16_f32 v124, v124, v125
	v_cvt_pk_bf16_f32 v125, v126, v127
	v_cvt_pk_bf16_f32 v126, v120, v121
	v_cvt_pk_bf16_f32 v127, v122, v123
	global_store_dwordx4 v[146:147], v[124:127], off nt
	v_cvt_pk_bf16_f32 v112, v112, v113
	v_cvt_pk_bf16_f32 v113, v114, v115
	v_cvt_pk_bf16_f32 v114, v104, v105
	v_or_b32_e32 v104, 16, v143
	v_cvt_pk_bf16_f32 v115, v106, v107
	global_store_dwordx4 v[146:147], v[112:115], off offset:256 nt
	s_andn2_b64 vcc, exec, s[38:39]
	s_mov_b64 s[38:39], -1
	v_mad_i64_i32 v[112:113], s[30:31], v104, s91, v[144:145]
	v_cvt_pk_bf16_f32 v104, v116, v117
	v_cvt_pk_bf16_f32 v105, v118, v119
	v_cvt_pk_bf16_f32 v106, v108, v109
	v_cvt_pk_bf16_f32 v107, v110, v111
	global_store_dwordx4 v[112:113], v[104:107], off nt
	v_cvt_pk_bf16_f32 v96, v96, v97
	v_cvt_pk_bf16_f32 v97, v98, v99
	v_cvt_pk_bf16_f32 v98, v88, v89
	v_or_b32_e32 v88, 32, v143
	v_cvt_pk_bf16_f32 v99, v90, v91
	global_store_dwordx4 v[112:113], v[96:99], off offset:256 nt
	s_movk_i32 s52, 0x1fff
	s_mov_b32 s53, 0x7ffff
	v_mad_i64_i32 v[96:97], s[30:31], v88, s91, v[144:145]
	v_cvt_pk_bf16_f32 v88, v100, v101
	v_cvt_pk_bf16_f32 v89, v102, v103
	v_cvt_pk_bf16_f32 v90, v92, v93
	v_cvt_pk_bf16_f32 v91, v94, v95
	global_store_dwordx4 v[96:97], v[88:91], off nt
	v_cvt_pk_bf16_f32 v80, v80, v81
	v_cvt_pk_bf16_f32 v81, v82, v83
	v_cvt_pk_bf16_f32 v82, v72, v73
	v_or_b32_e32 v72, 48, v143
	v_cvt_pk_bf16_f32 v83, v74, v75
	global_store_dwordx4 v[96:97], v[80:83], off offset:256 nt
	s_mov_b64 s[34:35], 0x800
	s_nop 0
	v_mad_i64_i32 v[80:81], s[30:31], v72, s91, v[144:145]
	v_cvt_pk_bf16_f32 v72, v84, v85
	v_cvt_pk_bf16_f32 v73, v86, v87
	v_cvt_pk_bf16_f32 v74, v76, v77
	v_cvt_pk_bf16_f32 v75, v78, v79
	global_store_dwordx4 v[80:81], v[72:75], off nt
	v_cvt_pk_bf16_f32 v68, v68, v69
	v_cvt_pk_bf16_f32 v69, v70, v71
	v_cvt_pk_bf16_f32 v70, v64, v65
	v_add_u32_e32 v64, 0x80, v143
	v_mad_i64_i32 v[64:65], s[30:31], v64, s91, v[144:145]
	v_cvt_pk_bf16_f32 v71, v66, v67
	global_store_dwordx4 v[80:81], v[68:71], off offset:256 nt
	v_cvt_pk_bf16_f32 v60, v60, v61
	v_cvt_pk_bf16_f32 v61, v62, v63
	v_cvt_pk_bf16_f32 v62, v56, v57
	v_cvt_pk_bf16_f32 v63, v58, v59
	global_store_dwordx4 v[64:65], v[60:63], off nt
	v_cvt_pk_bf16_f32 v48, v48, v49
	v_cvt_pk_bf16_f32 v49, v50, v51
	v_cvt_pk_bf16_f32 v50, v40, v41
	v_add_u32_e32 v40, 0x90, v143
	v_cvt_pk_bf16_f32 v51, v42, v43
	global_store_dwordx4 v[64:65], v[48:51], off offset:256 nt
	s_nop 1
	v_mad_i64_i32 v[48:49], s[30:31], v40, s91, v[144:145]
	v_cvt_pk_bf16_f32 v40, v52, v53
	v_cvt_pk_bf16_f32 v41, v54, v55
	v_cvt_pk_bf16_f32 v42, v44, v45
	v_cvt_pk_bf16_f32 v43, v46, v47
	global_store_dwordx4 v[48:49], v[40:43], off nt
	v_cvt_pk_bf16_f32 v32, v32, v33
	v_cvt_pk_bf16_f32 v33, v34, v35
	v_cvt_pk_bf16_f32 v34, v24, v25
	v_add_u32_e32 v24, 0xa0, v143
	v_cvt_pk_bf16_f32 v35, v26, v27
	global_store_dwordx4 v[48:49], v[32:35], off offset:256 nt
	s_nop 1
	v_mad_i64_i32 v[32:33], s[30:31], v24, s91, v[144:145]
	v_cvt_pk_bf16_f32 v24, v36, v37
	v_cvt_pk_bf16_f32 v25, v38, v39
	v_cvt_pk_bf16_f32 v26, v28, v29
	v_cvt_pk_bf16_f32 v27, v30, v31
	global_store_dwordx4 v[32:33], v[24:27], off nt
	v_cvt_pk_bf16_f32 v16, v16, v17
	v_cvt_pk_bf16_f32 v17, v18, v19
	v_cvt_pk_bf16_f32 v18, v8, v9
	v_add_u32_e32 v8, 0xb0, v143
	v_cvt_pk_bf16_f32 v19, v10, v11
	global_store_dwordx4 v[32:33], v[16:19], off offset:256 nt
	s_nop 1
	v_mad_i64_i32 v[16:17], s[30:31], v8, s91, v[144:145]
	v_cvt_pk_bf16_f32 v8, v20, v21
	v_cvt_pk_bf16_f32 v9, v22, v23
	v_cvt_pk_bf16_f32 v10, v12, v13
	v_cvt_pk_bf16_f32 v11, v14, v15
	global_store_dwordx4 v[16:17], v[8:11], off nt
	v_cvt_pk_bf16_f32 v4, v4, v5
	v_cvt_pk_bf16_f32 v5, v6, v7
	v_cvt_pk_bf16_f32 v6, v0, v1
	v_cvt_pk_bf16_f32 v7, v2, v3
	global_store_dwordx4 v[16:17], v[4:7], off offset:256 nt
	s_cbranch_vccnz .LBB0_94
	s_andn2_b64 vcc, exec, s[14:15]
	s_cbranch_vccnz .LBB0_93
	s_barrier
	s_branch .LBB0_93

.LBB0_802:
	v_mul_f32_e32 v143, 0xbfb8aa3b, v124
	v_exp_f32_e32 v143, v143
	v_lshl_or_b32 v144, s31, 7, v140
	v_lshl_add_u32 v142, s44, 8, v138
	v_ashrrev_i32_e32 v145, 31, v144
	v_add_f32_e32 v143, 1.0, v143
	v_rcp_f32_e32 v143, v143
	s_movk_i32 s17, 0x1600
	s_mov_b64 s[44:45], -1
	s_andn2_b64 vcc, exec, s[38:39]
	v_mul_f32_e32 v124, v124, v143
	v_mul_f32_e32 v120, v124, v120
	v_mul_f32_e32 v124, 0xbfb8aa3b, v116
	v_exp_f32_e32 v124, v124
	s_movk_i32 s52, 0x1fff
	s_mov_b32 s53, 0x7ffff
	v_add_f32_e32 v124, 1.0, v124
	v_rcp_f32_e32 v124, v124
	s_nop 0
	v_mul_f32_e32 v116, v116, v124
	v_mul_f32_e32 v112, v116, v112
	v_mul_f32_e32 v116, 0xbfb8aa3b, v125
	v_exp_f32_e32 v116, v116
	s_nop 0
	v_add_f32_e32 v116, 1.0, v116
	v_rcp_f32_e32 v116, v116
	s_nop 0
	v_mul_f32_e32 v116, v125, v116
	v_mul_f32_e32 v116, v116, v121
	v_mul_f32_e32 v121, 0xbfb8aa3b, v117
	v_exp_f32_e32 v121, v121
	v_cvt_pk_bf16_f32 v116, v120, v116
	s_nop 0
	v_add_f32_e32 v121, 1.0, v121
	v_rcp_f32_e32 v121, v121
	s_nop 0
	v_mul_f32_e32 v117, v117, v121
	v_mul_f32_e32 v121, 0xbfb8aa3b, v118
	v_exp_f32_e32 v121, v121
	v_mul_f32_e32 v113, v117, v113
	v_mul_f32_e32 v117, 0xbfb8aa3b, v126
	v_exp_f32_e32 v117, v117
	v_add_f32_e32 v121, 1.0, v121
	v_rcp_f32_e32 v121, v121
	v_add_f32_e32 v117, 1.0, v117
	v_rcp_f32_e32 v117, v117
	v_mul_f32_e32 v118, v118, v121
	v_mul_f32_e32 v114, v118, v114
	v_mul_f32_e32 v118, 0xbfb8aa3b, v127
	v_exp_f32_e32 v118, v118
	v_mul_f32_e32 v121, 0xbfb8aa3b, v119
	v_exp_f32_e32 v121, v121
	v_mul_f32_e32 v117, v126, v117
	v_add_f32_e32 v118, 1.0, v118
	v_rcp_f32_e32 v118, v118
	v_add_f32_e32 v121, 1.0, v121
	v_rcp_f32_e32 v121, v121
	v_mul_f32_e32 v117, v117, v122
	v_mul_f32_e32 v118, v127, v118
	v_mul_f32_e32 v118, v118, v123
	v_mul_f32_e32 v119, v119, v121
	v_mul_f32_e32 v115, v119, v115
	v_cvt_pk_bf16_f32 v117, v117, v118
	v_cvt_pk_bf16_f32 v118, v112, v113
	v_mov_b64_e32 v[112:113], s[12:13]
	v_cvt_pk_bf16_f32 v119, v114, v115
	v_mad_i64_i32 v[120:121], s[34:35], v142, s17, v[112:113]
	v_lshlrev_b64 v[114:115], 1, v[144:145]
	v_lshl_add_u64 v[120:121], v[120:121], 0, v[114:115]
	global_store_dwordx4 v[120:121], v[116:119], off nt
	s_nop 1
	v_mul_f32_e32 v116, 0xbfb8aa3b, v108
	v_exp_f32_e32 v116, v116
	s_nop 0
	v_add_f32_e32 v116, 1.0, v116
	v_rcp_f32_e32 v116, v116
	s_nop 0
	v_mul_f32_e32 v108, v108, v116
	v_mul_f32_e32 v104, v108, v104
	v_mul_f32_e32 v108, 0xbfb8aa3b, v100
	v_exp_f32_e32 v108, v108
	s_nop 0
	v_add_f32_e32 v108, 1.0, v108
	v_rcp_f32_e32 v108, v108
	s_nop 0
	v_mul_f32_e32 v100, v100, v108
	v_mul_f32_e32 v100, v100, v96
	v_mul_f32_e32 v96, 0xbfb8aa3b, v109
	v_exp_f32_e32 v96, v96
	s_nop 0
	v_add_f32_e32 v96, 1.0, v96
	v_rcp_f32_e32 v96, v96
	s_nop 0
	v_mul_f32_e32 v96, v109, v96
	v_mul_f32_e32 v96, v96, v105
	v_mul_f32_e32 v105, 0xbfb8aa3b, v101
	v_exp_f32_e32 v105, v105
	v_cvt_pk_bf16_f32 v96, v104, v96
	s_nop 0
	v_add_f32_e32 v105, 1.0, v105
	v_rcp_f32_e32 v105, v105
	s_nop 0
	v_mul_f32_e32 v101, v101, v105
	v_mul_f32_e32 v105, 0xbfb8aa3b, v102
	v_exp_f32_e32 v105, v105
	v_mul_f32_e32 v101, v101, v97
	v_mul_f32_e32 v97, 0xbfb8aa3b, v110
	v_exp_f32_e32 v97, v97
	v_add_f32_e32 v105, 1.0, v105
	v_rcp_f32_e32 v105, v105
	v_add_f32_e32 v97, 1.0, v97
	v_rcp_f32_e32 v97, v97
	v_mul_f32_e32 v102, v102, v105
	v_mul_f32_e32 v102, v102, v98
	v_mul_f32_e32 v98, 0xbfb8aa3b, v111
	v_exp_f32_e32 v98, v98
	v_mul_f32_e32 v105, 0xbfb8aa3b, v103
	v_exp_f32_e32 v105, v105
	v_mul_f32_e32 v97, v110, v97
	v_add_f32_e32 v98, 1.0, v98
	v_rcp_f32_e32 v98, v98
	v_add_f32_e32 v105, 1.0, v105
	v_rcp_f32_e32 v105, v105
	v_mul_f32_e32 v97, v97, v106
	v_mul_f32_e32 v98, v111, v98
	v_mul_f32_e32 v98, v98, v107
	v_cvt_pk_bf16_f32 v97, v97, v98
	v_cvt_pk_bf16_f32 v98, v100, v101
	v_or_b32_e32 v100, 16, v142
	v_mul_f32_e32 v103, v103, v105
	v_mad_i64_i32 v[100:101], s[34:35], v100, s17, v[112:113]
	v_mul_f32_e32 v99, v103, v99
	v_lshl_add_u64 v[100:101], v[100:101], 0, v[114:115]
	v_cvt_pk_bf16_f32 v99, v102, v99
	global_store_dwordx4 v[100:101], v[96:99], off nt
	s_nop 1
	v_mul_f32_e32 v96, 0xbfb8aa3b, v92
	v_exp_f32_e32 v96, v96
	s_nop 0
	v_add_f32_e32 v96, 1.0, v96
	v_rcp_f32_e32 v96, v96
	s_nop 0
	v_mul_f32_e32 v92, v92, v96
	v_mul_f32_e32 v88, v92, v88
	v_mul_f32_e32 v92, 0xbfb8aa3b, v84
	v_exp_f32_e32 v92, v92
	s_nop 0
	v_add_f32_e32 v92, 1.0, v92
	v_rcp_f32_e32 v92, v92
	s_nop 0
	v_mul_f32_e32 v84, v84, v92
	v_mul_f32_e32 v84, v84, v80
	v_mul_f32_e32 v80, 0xbfb8aa3b, v93
	v_exp_f32_e32 v80, v80
	s_nop 0
	v_add_f32_e32 v80, 1.0, v80
	v_rcp_f32_e32 v80, v80
	s_nop 0
	v_mul_f32_e32 v80, v93, v80
	v_mul_f32_e32 v80, v80, v89
	v_mul_f32_e32 v89, 0xbfb8aa3b, v85
	v_exp_f32_e32 v89, v89
	v_cvt_pk_bf16_f32 v80, v88, v80
	s_nop 0
	v_add_f32_e32 v89, 1.0, v89
	v_rcp_f32_e32 v89, v89
	s_nop 0
	v_mul_f32_e32 v85, v85, v89
	v_mul_f32_e32 v89, 0xbfb8aa3b, v86
	v_exp_f32_e32 v89, v89
	v_mul_f32_e32 v85, v85, v81
	v_mul_f32_e32 v81, 0xbfb8aa3b, v94
	v_exp_f32_e32 v81, v81
	v_add_f32_e32 v89, 1.0, v89
	v_rcp_f32_e32 v89, v89
	v_add_f32_e32 v81, 1.0, v81
	v_rcp_f32_e32 v81, v81
	v_mul_f32_e32 v86, v86, v89
	v_mul_f32_e32 v86, v86, v82
	v_mul_f32_e32 v82, 0xbfb8aa3b, v95
	v_exp_f32_e32 v82, v82
	v_mul_f32_e32 v89, 0xbfb8aa3b, v87
	v_exp_f32_e32 v89, v89
	v_mul_f32_e32 v81, v94, v81
	v_add_f32_e32 v82, 1.0, v82
	v_rcp_f32_e32 v82, v82
	v_add_f32_e32 v89, 1.0, v89
	v_rcp_f32_e32 v89, v89
	v_mul_f32_e32 v81, v81, v90
	v_mul_f32_e32 v82, v95, v82
	v_mul_f32_e32 v82, v82, v91
	v_cvt_pk_bf16_f32 v81, v81, v82
	v_cvt_pk_bf16_f32 v82, v84, v85
	v_or_b32_e32 v84, 32, v142
	v_mul_f32_e32 v87, v87, v89
	v_mad_i64_i32 v[84:85], s[34:35], v84, s17, v[112:113]
	v_mul_f32_e32 v83, v87, v83
	v_lshl_add_u64 v[84:85], v[84:85], 0, v[114:115]
	v_cvt_pk_bf16_f32 v83, v86, v83
	global_store_dwordx4 v[84:85], v[80:83], off nt
	s_nop 1
	v_mul_f32_e32 v80, 0xbfb8aa3b, v76
	v_exp_f32_e32 v80, v80
	s_nop 0
	v_add_f32_e32 v80, 1.0, v80
	v_rcp_f32_e32 v80, v80
	s_nop 0
	v_mul_f32_e32 v76, v76, v80
	v_mul_f32_e32 v72, v76, v72
	v_mul_f32_e32 v76, 0xbfb8aa3b, v68
	v_exp_f32_e32 v76, v76
	s_nop 0
	v_add_f32_e32 v76, 1.0, v76
	v_rcp_f32_e32 v76, v76
	s_nop 0
	v_mul_f32_e32 v68, v68, v76
	v_mul_f32_e32 v68, v68, v64
	v_mul_f32_e32 v64, 0xbfb8aa3b, v77
	v_exp_f32_e32 v64, v64
	s_nop 0
	v_add_f32_e32 v64, 1.0, v64
	v_rcp_f32_e32 v64, v64
	s_nop 0
	v_mul_f32_e32 v64, v77, v64
	v_mul_f32_e32 v64, v64, v73
	v_mul_f32_e32 v73, 0xbfb8aa3b, v69
	v_exp_f32_e32 v73, v73
	v_cvt_pk_bf16_f32 v64, v72, v64
	s_nop 0
	v_add_f32_e32 v73, 1.0, v73
	v_rcp_f32_e32 v73, v73
	s_nop 0
	v_mul_f32_e32 v69, v69, v73
	v_mul_f32_e32 v73, 0xbfb8aa3b, v70
	v_exp_f32_e32 v73, v73
	v_mul_f32_e32 v69, v69, v65
	v_mul_f32_e32 v65, 0xbfb8aa3b, v78
	v_exp_f32_e32 v65, v65
	v_add_f32_e32 v73, 1.0, v73
	v_rcp_f32_e32 v73, v73
	v_add_f32_e32 v65, 1.0, v65
	v_rcp_f32_e32 v65, v65
	v_mul_f32_e32 v70, v70, v73
	v_mul_f32_e32 v70, v70, v66
	v_mul_f32_e32 v66, 0xbfb8aa3b, v79
	v_exp_f32_e32 v66, v66
	v_mul_f32_e32 v73, 0xbfb8aa3b, v71
	v_exp_f32_e32 v73, v73
	v_mul_f32_e32 v65, v78, v65
	v_add_f32_e32 v66, 1.0, v66
	v_rcp_f32_e32 v66, v66
	v_add_f32_e32 v73, 1.0, v73
	v_rcp_f32_e32 v73, v73
	v_mul_f32_e32 v65, v65, v74
	v_mul_f32_e32 v66, v79, v66
	v_mul_f32_e32 v66, v66, v75
	v_cvt_pk_bf16_f32 v65, v65, v66
	v_cvt_pk_bf16_f32 v66, v68, v69
	v_or_b32_e32 v68, 48, v142
	v_mul_f32_e32 v71, v71, v73
	v_mad_i64_i32 v[68:69], s[34:35], v68, s17, v[112:113]
	v_mul_f32_e32 v67, v71, v67
	v_lshl_add_u64 v[68:69], v[68:69], 0, v[114:115]
	v_cvt_pk_bf16_f32 v67, v70, v67
	global_store_dwordx4 v[68:69], v[64:67], off nt
	s_nop 1
	v_mul_f32_e32 v65, 0xbfb8aa3b, v60
	v_exp_f32_e32 v65, v65
	v_add_u32_e32 v64, 0x80, v142
	v_add_f32_e32 v65, 1.0, v65
	v_rcp_f32_e32 v65, v65
	s_nop 0
	v_mul_f32_e32 v60, v60, v65
	v_mul_f32_e32 v56, v60, v56
	v_mul_f32_e32 v60, 0xbfb8aa3b, v52
	v_exp_f32_e32 v60, v60
	s_nop 0
	v_add_f32_e32 v60, 1.0, v60
	v_rcp_f32_e32 v60, v60
	s_nop 0
	v_mul_f32_e32 v52, v52, v60
	v_mul_f32_e32 v52, v52, v48
	v_mul_f32_e32 v48, 0xbfb8aa3b, v61
	v_exp_f32_e32 v48, v48
	s_nop 0
	v_add_f32_e32 v48, 1.0, v48
	v_rcp_f32_e32 v48, v48
	s_nop 0
	v_mul_f32_e32 v48, v61, v48
	v_mul_f32_e32 v48, v48, v57
	v_mul_f32_e32 v57, 0xbfb8aa3b, v53
	v_exp_f32_e32 v57, v57
	v_cvt_pk_bf16_f32 v48, v56, v48
	s_nop 0
	v_add_f32_e32 v57, 1.0, v57
	v_rcp_f32_e32 v57, v57
	s_nop 0
	v_mul_f32_e32 v53, v53, v57
	v_mul_f32_e32 v57, 0xbfb8aa3b, v54
	v_exp_f32_e32 v57, v57
	v_mul_f32_e32 v53, v53, v49
	v_mul_f32_e32 v49, 0xbfb8aa3b, v62
	v_exp_f32_e32 v49, v49
	v_add_f32_e32 v57, 1.0, v57
	v_rcp_f32_e32 v57, v57
	v_add_f32_e32 v49, 1.0, v49
	v_rcp_f32_e32 v49, v49
	v_mul_f32_e32 v54, v54, v57
	v_mul_f32_e32 v54, v54, v50
	v_mul_f32_e32 v50, 0xbfb8aa3b, v63
	v_exp_f32_e32 v50, v50
	v_mul_f32_e32 v57, 0xbfb8aa3b, v55
	v_exp_f32_e32 v57, v57
	v_mul_f32_e32 v49, v62, v49
	v_add_f32_e32 v50, 1.0, v50
	v_rcp_f32_e32 v50, v50
	v_add_f32_e32 v57, 1.0, v57
	v_rcp_f32_e32 v57, v57
	v_mul_f32_e32 v49, v49, v58
	v_mul_f32_e32 v50, v63, v50
	v_mul_f32_e32 v50, v50, v59
	v_mul_f32_e32 v55, v55, v57
	v_cvt_pk_bf16_f32 v49, v49, v50
	v_cvt_pk_bf16_f32 v50, v52, v53
	v_mad_i64_i32 v[52:53], s[34:35], v64, s17, v[112:113]
	v_mul_f32_e32 v51, v55, v51
	v_lshl_add_u64 v[52:53], v[52:53], 0, v[114:115]
	v_cvt_pk_bf16_f32 v51, v54, v51
	global_store_dwordx4 v[52:53], v[48:51], off nt
	s_nop 1
	v_mul_f32_e32 v48, 0xbfb8aa3b, v44
	v_exp_f32_e32 v48, v48
	s_nop 0
	v_add_f32_e32 v48, 1.0, v48
	v_rcp_f32_e32 v48, v48
	s_nop 0
	v_mul_f32_e32 v44, v44, v48
	v_mul_f32_e32 v40, v44, v40
	v_mul_f32_e32 v44, 0xbfb8aa3b, v36
	v_exp_f32_e32 v44, v44
	s_nop 0
	v_add_f32_e32 v44, 1.0, v44
	v_rcp_f32_e32 v44, v44
	s_nop 0
	v_mul_f32_e32 v36, v36, v44
	v_mul_f32_e32 v36, v36, v32
	v_mul_f32_e32 v32, 0xbfb8aa3b, v45
	v_exp_f32_e32 v32, v32
	s_nop 0
	v_add_f32_e32 v32, 1.0, v32
	v_rcp_f32_e32 v32, v32
	s_nop 0
	v_mul_f32_e32 v32, v45, v32
	v_mul_f32_e32 v32, v32, v41
	v_mul_f32_e32 v41, 0xbfb8aa3b, v37
	v_exp_f32_e32 v41, v41
	v_cvt_pk_bf16_f32 v32, v40, v32
	s_nop 0
	v_add_f32_e32 v41, 1.0, v41
	v_rcp_f32_e32 v41, v41
	s_nop 0
	v_mul_f32_e32 v37, v37, v41
	v_mul_f32_e32 v41, 0xbfb8aa3b, v38
	v_exp_f32_e32 v41, v41
	v_mul_f32_e32 v37, v37, v33
	v_mul_f32_e32 v33, 0xbfb8aa3b, v46
	v_exp_f32_e32 v33, v33
	v_add_f32_e32 v41, 1.0, v41
	v_rcp_f32_e32 v41, v41
	v_add_f32_e32 v33, 1.0, v33
	v_rcp_f32_e32 v33, v33
	v_mul_f32_e32 v38, v38, v41
	v_mul_f32_e32 v38, v38, v34
	v_mul_f32_e32 v34, 0xbfb8aa3b, v47
	v_exp_f32_e32 v34, v34
	v_mul_f32_e32 v41, 0xbfb8aa3b, v39
	v_exp_f32_e32 v41, v41
	v_mul_f32_e32 v33, v46, v33
	v_add_f32_e32 v34, 1.0, v34
	v_rcp_f32_e32 v34, v34
	v_add_f32_e32 v41, 1.0, v41
	v_rcp_f32_e32 v41, v41
	v_mul_f32_e32 v33, v33, v42
	v_mul_f32_e32 v34, v47, v34
	v_mul_f32_e32 v34, v34, v43
	v_cvt_pk_bf16_f32 v33, v33, v34
	v_cvt_pk_bf16_f32 v34, v36, v37
	v_add_u32_e32 v36, 0x90, v142
	v_mul_f32_e32 v39, v39, v41
	v_mad_i64_i32 v[36:37], s[34:35], v36, s17, v[112:113]
	v_mul_f32_e32 v35, v39, v35
	v_lshl_add_u64 v[36:37], v[36:37], 0, v[114:115]
	v_cvt_pk_bf16_f32 v35, v38, v35
	global_store_dwordx4 v[36:37], v[32:35], off nt
	s_nop 1
	v_mul_f32_e32 v32, 0xbfb8aa3b, v28
	v_exp_f32_e32 v32, v32
	s_nop 0
	v_add_f32_e32 v32, 1.0, v32
	v_rcp_f32_e32 v32, v32
	s_nop 0
	v_mul_f32_e32 v28, v28, v32
	v_mul_f32_e32 v24, v28, v24
	v_mul_f32_e32 v28, 0xbfb8aa3b, v20
	v_exp_f32_e32 v28, v28
	s_nop 0
	v_add_f32_e32 v28, 1.0, v28
	v_rcp_f32_e32 v28, v28
	s_nop 0
	v_mul_f32_e32 v20, v20, v28
	v_mul_f32_e32 v20, v20, v16
	v_mul_f32_e32 v16, 0xbfb8aa3b, v29
	v_exp_f32_e32 v16, v16
	s_nop 0
	v_add_f32_e32 v16, 1.0, v16
	v_rcp_f32_e32 v16, v16
	s_nop 0
	v_mul_f32_e32 v16, v29, v16
	v_mul_f32_e32 v16, v16, v25
	v_mul_f32_e32 v25, 0xbfb8aa3b, v21
	v_exp_f32_e32 v25, v25
	v_cvt_pk_bf16_f32 v16, v24, v16
	s_nop 0
	v_add_f32_e32 v25, 1.0, v25
	v_rcp_f32_e32 v25, v25
	s_nop 0
	v_mul_f32_e32 v21, v21, v25
	v_mul_f32_e32 v25, 0xbfb8aa3b, v22
	v_exp_f32_e32 v25, v25
	v_mul_f32_e32 v21, v21, v17
	v_mul_f32_e32 v17, 0xbfb8aa3b, v30
	v_exp_f32_e32 v17, v17
	v_add_f32_e32 v25, 1.0, v25
	v_rcp_f32_e32 v25, v25
	v_add_f32_e32 v17, 1.0, v17
	v_rcp_f32_e32 v17, v17
	v_mul_f32_e32 v22, v22, v25
	v_mul_f32_e32 v22, v22, v18
	v_mul_f32_e32 v18, 0xbfb8aa3b, v31
	v_exp_f32_e32 v18, v18
	v_mul_f32_e32 v25, 0xbfb8aa3b, v23
	v_exp_f32_e32 v25, v25
	v_mul_f32_e32 v17, v30, v17
	v_add_f32_e32 v18, 1.0, v18
	v_rcp_f32_e32 v18, v18
	v_add_f32_e32 v25, 1.0, v25
	v_rcp_f32_e32 v25, v25
	v_mul_f32_e32 v17, v17, v26
	v_mul_f32_e32 v18, v31, v18
	v_mul_f32_e32 v18, v18, v27
	v_cvt_pk_bf16_f32 v17, v17, v18
	v_cvt_pk_bf16_f32 v18, v20, v21
	v_add_u32_e32 v20, 0xa0, v142
	v_mul_f32_e32 v23, v23, v25
	v_mad_i64_i32 v[20:21], s[34:35], v20, s17, v[112:113]
	v_mul_f32_e32 v19, v23, v19
	v_lshl_add_u64 v[20:21], v[20:21], 0, v[114:115]
	v_cvt_pk_bf16_f32 v19, v22, v19
	global_store_dwordx4 v[20:21], v[16:19], off nt
	s_nop 1
	v_mul_f32_e32 v16, 0xbfb8aa3b, v12
	v_exp_f32_e32 v16, v16
	s_nop 0
	v_add_f32_e32 v16, 1.0, v16
	v_rcp_f32_e32 v16, v16
	s_nop 0
	v_mul_f32_e32 v12, v12, v16
	v_mul_f32_e32 v8, v12, v8
	v_mul_f32_e32 v12, 0xbfb8aa3b, v4
	v_exp_f32_e32 v12, v12
	s_nop 0
	v_add_f32_e32 v12, 1.0, v12
	v_rcp_f32_e32 v12, v12
	s_nop 0
	v_mul_f32_e32 v4, v4, v12
	v_mul_f32_e32 v4, v4, v0
	v_mul_f32_e32 v0, 0xbfb8aa3b, v13
	v_exp_f32_e32 v0, v0
	s_nop 0
	v_add_f32_e32 v0, 1.0, v0
	v_rcp_f32_e32 v0, v0
	s_nop 0
	v_mul_f32_e32 v0, v13, v0
	v_mul_f32_e32 v0, v0, v9
	v_mul_f32_e32 v9, 0xbfb8aa3b, v5
	v_exp_f32_e32 v9, v9
	v_cvt_pk_bf16_f32 v0, v8, v0
	s_nop 0
	v_add_f32_e32 v9, 1.0, v9
	v_rcp_f32_e32 v9, v9
	s_nop 0
	v_mul_f32_e32 v5, v5, v9
	v_mul_f32_e32 v9, 0xbfb8aa3b, v6
	v_exp_f32_e32 v9, v9
	v_mul_f32_e32 v5, v5, v1
	v_mul_f32_e32 v1, 0xbfb8aa3b, v14
	v_exp_f32_e32 v1, v1
	v_add_f32_e32 v9, 1.0, v9
	v_rcp_f32_e32 v9, v9
	v_add_f32_e32 v1, 1.0, v1
	v_rcp_f32_e32 v1, v1
	v_mul_f32_e32 v6, v6, v9
	v_mul_f32_e32 v6, v6, v2
	v_mul_f32_e32 v2, 0xbfb8aa3b, v15
	v_exp_f32_e32 v2, v2
	v_mul_f32_e32 v9, 0xbfb8aa3b, v7
	v_exp_f32_e32 v9, v9
	v_mul_f32_e32 v1, v14, v1
	v_add_f32_e32 v2, 1.0, v2
	v_rcp_f32_e32 v2, v2
	v_add_f32_e32 v9, 1.0, v9
	v_rcp_f32_e32 v9, v9
	v_mul_f32_e32 v1, v1, v10
	v_mul_f32_e32 v2, v15, v2
	v_mul_f32_e32 v2, v2, v11
	v_cvt_pk_bf16_f32 v1, v1, v2
	v_cvt_pk_bf16_f32 v2, v4, v5
	v_add_u32_e32 v4, 0xb0, v142
	v_mul_f32_e32 v7, v7, v9
	v_mad_i64_i32 v[4:5], s[34:35], v4, s17, v[112:113]
	v_mul_f32_e32 v3, v7, v3
	v_lshl_add_u64 v[4:5], v[4:5], 0, v[114:115]
	v_cvt_pk_bf16_f32 v3, v6, v3
	global_store_dwordx4 v[4:5], v[0:3], off nt
	s_cbranch_vccnz .LBB0_795
	s_andn2_b64 vcc, exec, s[8:9]
	s_cbranch_vccnz .LBB0_794
	s_barrier
	s_branch .LBB0_794
